# PROJ phase: permute workgroup index for 2nd/3rd GEMM so extra rounds land on different WGs
# baseline (speedup 1.0000x reference)
.LBB0_264:
	s_xor_b32 s62, s62, 0xf8
	s_and_b64 s[6:7], s[16:17], exec
	s_movk_i32 s0, 0x220
	s_cselect_b32 s96, s0, 0x88
	v_mov_b32_e32 v145, v191
	s_cmp_ge_i32 s62, s96
	v_readfirstlane_b32 s7, v145
	s_cbranch_scc1 .LBB0_280
	v_lshlrev_b32_e32 v0, 4, v145
	v_add_u32_e32 v1, 0x2000, v0
	v_ashrrev_i32_e32 v2, 31, v1
	v_lshrrev_b32_e32 v2, 22, v2
	v_add_u32_e32 v2, v1, v2
	v_ashrrev_i32_e32 v146, 10, v2
	v_mul_i32_i24_e32 v2, 0x400, v146
	v_sub_u32_e32 v1, v1, v2
	v_lshrrev_b32_e32 v2, 4, v1
	v_bitop3_b32 v1, v2, v1, 32 bitop3:0x6c
	v_ashrrev_i32_e32 v2, 31, v1
	v_lshrrev_b32_e32 v2, 26, v2
	v_add_u32_e32 v2, v1, v2
	v_lshlrev_b32_e32 v3, 3, v146
	v_ashrrev_i32_e32 v147, 6, v2
	v_and_b32_e32 v3, -16, v3
	v_add_u32_e32 v3, v147, v3
	v_and_b32_e32 v4, 3, v147
	s_mov_b32 s6, 0x1fffe0
	v_lshrrev_b32_e32 v5, 2, v3
	v_lshlrev_b32_e32 v6, 1, v3
	v_and_b32_e32 v2, 0xc0, v2
	v_and_or_b32 v4, v3, s6, v4
	v_and_b32_e32 v5, 4, v5
	v_and_b32_e32 v6, 24, v6
	v_sub_u32_e32 v1, v1, v2
	v_or3_b32 v4, v4, v5, v6
	v_lshlrev_b32_e32 v5, 5, v146
	v_ashrrev_i16_sdwa v1, v231, sext(v1) dst_sel:DWORD dst_unused:UNUSED_PAD src0_sel:DWORD src1_sel:BYTE_0
	v_and_b32_e32 v5, 32, v5
	v_bfe_i32 v148, v1, 0, 16
	v_add_lshl_u32 v1, v5, v148, 1
	v_lshl_add_u32 v130, v4, 11, v1
	v_lshl_add_u32 v132, v3, 11, v1
	v_bfe_i32 v1, v145, 27, 1
	v_lshrrev_b32_e32 v1, 22, v1
	v_add_u32_e32 v1, v0, v1
	v_and_b32_e32 v1, 0xfffffc00, v1
	v_sub_u32_e32 v0, v0, v1
	s_and_b64 s[8:9], s[16:17], exec
	s_mov_b32 s0, 0x400000
	v_lshrrev_b32_e32 v1, 4, v0
	v_ashrrev_i32_e32 v2, 31, v145
	s_cselect_b32 s0, s0, 0x280000
	v_bitop3_b32 v0, v1, v0, 32 bitop3:0x6c
	v_lshrrev_b32_e32 v2, 26, v2
	s_add_u32 s0, s1, s0
	v_ashrrev_i32_e32 v1, 31, v0
	v_add_u32_e32 v2, v145, v2
	s_addc_u32 s1, s4, 0
	s_ashr_i32 s21, s7, 6
	v_lshrrev_b32_e32 v1, 26, v1
	v_ashrrev_i32_e32 v150, 6, v2
	s_ashr_i32 s24, s7, 8
	s_lshl_b32 s4, s21, 10
	v_add_u32_e32 v1, v0, v1
	v_lshlrev_b32_e32 v2, 3, v150
	s_and_b64 s[8:9], s[16:17], exec
	v_ashrrev_i32_e32 v149, 6, v1
	v_and_b32_e32 v2, -16, v2
	s_cselect_b32 s5, 4, 1
	v_add_u32_e32 v2, v149, v2
	v_and_b32_e32 v3, 3, v149
	s_ashr_i32 s41, s62, 31
	v_and_or_b32 v3, v2, s6, v3
	s_lshr_b32 s6, s41, 29
	s_add_i32 s6, s62, s6
	s_lshr_b32 s40, s96, 3
	s_ashr_i32 s8, s6, 3
	s_and_b32 s6, s6, -8
	s_sub_i32 s6, s62, s6
	s_add_i32 s42, s40, 1
	s_cmp_lt_i32 s6, 0
	s_cselect_b32 s9, s42, s40
	s_mul_i32 s6, s6, s9
	s_add_i32 s6, s6, s8
	s_mul_hi_i32 s8, s6, 0x78787879
	s_lshr_b32 s9, s8, 31
	s_ashr_i32 s8, s8, 9
	v_lshrrev_b32_e32 v4, 2, v2
	v_lshlrev_b32_e32 v5, 1, v2
	v_and_b32_e32 v1, 0xc0, v1
	s_add_i32 s8, s8, s9
	v_and_b32_e32 v4, 4, v4
	v_and_b32_e32 v5, 24, v5
	v_sub_u32_e32 v0, v0, v1
	s_lshl_b32 s10, s8, 3
	v_or3_b32 v3, v3, v4, v5
	v_lshlrev_b32_e32 v4, 5, v150
	v_ashrrev_i16_sdwa v0, v231, sext(v0) dst_sel:DWORD dst_unused:UNUSED_PAD src0_sel:DWORD src1_sel:BYTE_0
	s_sub_i32 s9, s5, s10
	v_and_b32_e32 v4, 32, v4
	v_bfe_i32 v151, v0, 0, 16
	s_min_i32 s11, s9, 8
	v_add_lshl_u32 v0, v4, v151, 1
	s_sext_i32_i16 s9, s11
	v_lshl_add_u32 v128, v3, 11, v0
	v_lshl_add_u32 v134, v2, 11, v0
	v_cvt_f32_i32_e32 v0, s9
	s_mulk_i32 s8, 0x440
	s_sub_i32 s18, s6, s8
	v_cvt_f32_i32_e32 v1, s18
	v_rcp_iflag_f32_e32 v2, v0
	s_xor_b32 s6, s18, s9
	s_ashr_i32 s6, s6, 30
	s_or_b32 s6, s6, 1
	v_mul_f32_e32 v2, v1, v2
	v_trunc_f32_e32 v2, v2
	v_fma_f32 v1, -v2, v0, v1
	v_cvt_i32_f32_e32 v2, v2
	v_cmp_ge_f32_e64 s[8:9], |v1|, |v0|
	s_and_b64 s[8:9], s[8:9], exec
	s_cselect_b32 s6, s6, 0
	v_readfirstlane_b32 s8, v2
	s_add_i32 s6, s8, s6
	s_mul_i32 s8, s6, s11
	s_sub_i32 s8, s18, s8
	s_sext_i32_i16 s8, s8
	s_add_i32 s18, s10, s8
	s_ashr_i32 s19, s18, 31
	s_lshl_b64 s[8:9], s[18:19], 19
	s_add_u32 s28, s0, s8
	s_addc_u32 s29, s1, s9
	s_bfe_i64 s[8:9], s[6:7], 0x100000
	s_lshl_b64 s[8:9], s[8:9], 19
	s_add_u32 s34, s50, s8
	s_addc_u32 s35, s51, s9
	s_add_i32 s19, s4, 0
	s_add_i32 m0, s19, 0x10000
	s_waitcnt vmcnt(0)
	v_mov_b32 v108, 0
	v_mov_b32 v116, 0
	v_mov_b32 v92, 0
	v_mov_b32 v100, 0
	v_mov_b32 v68, 0
	v_mov_b32 v76, 0
	v_mov_b32 v40, 0
	v_mov_b32 v44, 0
	v_mov_b32 v120, 0
	v_mov_b32 v124, 0
	v_mov_b32 v104, 0
	v_mov_b32 v112, 0
	v_mov_b32 v88, 0
	v_mov_b32 v96, 0
	v_mov_b32 v64, 0
	v_mov_b32 v72, 0
	v_mov_b32 v52, 0
	v_mov_b32 v60, 0
	v_mov_b32 v28, 0
	v_mov_b32 v36, 0
	v_mov_b32 v12, 0
	v_mov_b32 v16, 0
	v_mov_b32 v0, 0
	v_mov_b32 v4, 0
	v_mov_b32 v80, 0
	v_mov_b32 v84, 0
	v_mov_b32 v48, 0
	v_mov_b32 v56, 0
	v_mov_b32 v24, 0
	v_mov_b32 v32, 0
	v_mov_b32 v8, 0
	v_mov_b32 v20, 0
	global_load_lds_dwordx4 v128, s[34:35]
	s_add_i32 m0, s19, 0x12000
	s_add_u32 s8, s34, 0x40000
	global_load_lds_dwordx4 v130, s[34:35]
	s_addc_u32 s9, s35, 0
	s_add_i32 m0, s19, 0x14000
	s_add_i32 s43, s19, 0x2000
	global_load_lds_dwordx4 v128, s[8:9]
	s_add_i32 m0, s19, 0x16000
	v_mov_b32_e32 v131, v129
	global_load_lds_dwordx4 v130, s[8:9]
	s_mov_b32 m0, s19
	s_add_u32 s8, s28, 0x40000
	global_load_lds_dwordx4 v134, s[28:29]
	s_mov_b32 m0, s43
	s_addc_u32 s9, s29, 0
	s_add_i32 s46, s19, 0x4000
	global_load_lds_dwordx4 v132, s[28:29]
	s_mov_b32 m0, s46
	s_add_i32 s47, s19, 0x6000
	global_load_lds_dwordx4 v134, s[8:9]
	s_mov_b32 m0, s47
	v_mov_b32_e32 v135, v129
	global_load_lds_dwordx4 v132, s[8:9]
	v_mov_b32_e32 v133, v129
	s_cmp_eq_u32 s24, 1
	v_lshl_add_u64 v[142:143], s[34:35], 0, v[128:129]
	v_lshl_add_u64 v[140:141], s[34:35], 0, v[130:131]
	v_lshl_add_u64 v[136:137], s[28:29], 0, v[134:135]
	s_cselect_b64 s[8:9], -1, 0
	s_cmp_lg_u32 s24, 1
	v_lshl_add_u64 v[138:139], s[28:29], 0, v[132:133]
	s_cbranch_scc1 .LBB0_267
	s_barrier

.LBB0_335:
	s_xor_b32 s62, s62, 0xf8
	s_add_u32 s0, s2, 0x1a800000
	s_addc_u32 s1, s3, 0
	v_mov_b32_e32 v137, v191
	s_cmpk_lt_i32 s62, 0x220
	s_cselect_b64 s[8:9], -1, 0
	s_cmpk_gt_i32 s62, 0x21f
	v_readfirstlane_b32 s7, v137
	s_cbranch_scc1 .LBB0_351
	v_lshlrev_b32_e32 v0, 4, v137
	v_add_u32_e32 v1, 0x2000, v0
	v_ashrrev_i32_e32 v2, 31, v1
	v_lshrrev_b32_e32 v2, 22, v2
	v_add_u32_e32 v2, v1, v2
	v_ashrrev_i32_e32 v2, 10, v2
	v_mul_i32_i24_e32 v3, 0x400, v2
	v_sub_u32_e32 v1, v1, v3
	v_lshrrev_b32_e32 v3, 4, v1
	v_bitop3_b32 v1, v3, v1, 32 bitop3:0x6c
	v_ashrrev_i32_e32 v3, 31, v1
	v_lshrrev_b32_e32 v3, 26, v3
	v_add_u32_e32 v3, v1, v3
	v_lshlrev_b32_e32 v5, 3, v2
	v_ashrrev_i32_e32 v4, 6, v3
	v_and_b32_e32 v5, -16, v5
	v_and_b32_e32 v3, 0xc0, v3
	v_add_u32_e32 v5, v4, v5
	v_sub_u32_e32 v1, v1, v3
	v_and_b32_e32 v4, 3, v4
	s_mov_b32 s6, 0x7fffe0
	v_lshrrev_b32_e32 v6, 2, v5
	v_lshlrev_b32_e32 v7, 1, v5
	v_lshlrev_b32_e32 v2, 5, v2
	v_ashrrev_i16_sdwa v1, v231, sext(v1) dst_sel:DWORD dst_unused:UNUSED_PAD src0_sel:DWORD src1_sel:BYTE_0
	v_and_or_b32 v4, v5, s6, v4
	v_and_b32_e32 v6, 4, v6
	v_and_b32_e32 v7, 24, v7
	v_and_b32_e32 v2, 32, v2
	v_bfe_i32 v1, v1, 0, 16
	v_or3_b32 v4, v4, v6, v7
	v_add_lshl_u32 v1, v2, v1, 1
	v_lshl_add_u32 v130, v4, 9, v1
	v_lshl_add_u32 v132, v5, 9, v1
	v_bfe_i32 v1, v137, 27, 1
	v_lshrrev_b32_e32 v1, 22, v1
	v_add_u32_e32 v1, v0, v1
	v_and_b32_e32 v1, 0xfffffc00, v1
	v_sub_u32_e32 v0, v0, v1
	v_lshrrev_b32_e32 v1, 4, v0
	v_ashrrev_i32_e32 v3, 31, v137
	v_bitop3_b32 v0, v1, v0, 32 bitop3:0x6c
	v_lshrrev_b32_e32 v3, 26, v3
	v_ashrrev_i32_e32 v1, 31, v0
	v_add_u32_e32 v3, v137, v3
	v_lshrrev_b32_e32 v1, 26, v1
	v_ashrrev_i32_e32 v3, 6, v3
	v_add_u32_e32 v1, v0, v1
	v_lshlrev_b32_e32 v4, 3, v3
	s_add_u32 s4, s67, 0x23a0000
	v_ashrrev_i32_e32 v2, 6, v1
	v_and_b32_e32 v4, -16, v4
	s_addc_u32 s5, s94, 0
	v_add_u32_e32 v4, v2, v4
	v_and_b32_e32 v2, 3, v2
	s_ashr_i32 s41, s62, 31
	v_and_or_b32 v2, v4, s6, v2
	s_lshr_b32 s6, s41, 29
	s_add_i32 s6, s62, s6
	s_ashr_i32 s15, s7, 6
	s_and_b32 s10, s6, -8
	s_ashr_i32 s14, s7, 8
	s_lshl_b32 s40, s15, 10
	s_sub_i32 s10, s62, s10
	s_cmp_lt_i32 s10, 0
	s_movk_i32 s11, 0x45
	s_cselect_b32 s11, s11, 0x44
	s_mul_i32 s10, s10, s11
	s_ashr_i32 s6, s6, 3
	s_add_i32 s6, s10, s6
	s_ashr_i32 s10, s6, 31
	s_lshr_b32 s10, s10, 27
	s_add_i32 s10, s6, s10
	s_ashr_i32 s11, s10, 5
	s_and_b32 s10, s10, 0xffe0
	s_sub_i32 s10, s6, s10
	s_bfe_i32 s6, s10, 0x80000
	s_bfe_u32 s6, s6, 0x3000c
	s_add_i32 s16, s10, s6
	s_bfe_i32 s6, s16, 0x80000
	s_and_b32 s16, s16, 0xf8
	s_sub_i32 s10, s10, s16
	s_lshl_b32 s11, s11, 3
	s_sext_i32_i8 s10, s10
	s_add_i32 s24, s11, s10
	s_sext_i32_i16 s6, s6
	s_ashr_i32 s25, s24, 31
	s_lshr_b32 s6, s6, 3
	s_lshl_b64 s[10:11], s[24:25], 17
	v_and_b32_e32 v1, 0xc0, v1
	s_add_u32 s34, s0, s10
	v_sub_u32_e32 v0, v0, v1
	s_addc_u32 s35, s1, s11
	s_bfe_i64 s[10:11], s[6:7], 0x100000
	v_lshrrev_b32_e32 v5, 2, v4
	v_lshlrev_b32_e32 v6, 1, v4
	v_lshlrev_b32_e32 v3, 5, v3
	v_ashrrev_i16_sdwa v0, v231, sext(v0) dst_sel:DWORD dst_unused:UNUSED_PAD src0_sel:DWORD src1_sel:BYTE_0
	s_lshl_b64 s[10:11], s[10:11], 17
	v_and_b32_e32 v5, 4, v5
	v_and_b32_e32 v6, 24, v6
	v_and_b32_e32 v3, 32, v3
	v_bfe_i32 v0, v0, 0, 16
	s_add_u32 s36, s4, s10
	v_or3_b32 v2, v2, v5, v6
	v_add_lshl_u32 v0, v3, v0, 1
	s_addc_u32 s37, s5, s11
	s_add_i32 s20, s40, 0
	v_lshl_add_u32 v128, v2, 9, v0
	s_add_i32 m0, s20, 0x10000
	v_lshl_add_u32 v134, v4, 9, v0
	v_mov_b32 v112, 0
	v_mov_b32 v116, 0
	s_waitcnt vmcnt(0)
	v_mov_b32 v96, 0
	v_mov_b32 v100, 0
	v_mov_b32 v72, 0
	v_mov_b32 v80, 0
	v_mov_b32 v40, 0
	v_mov_b32 v48, 0
	v_mov_b32 v120, 0
	v_mov_b32 v124, 0
	v_mov_b32 v104, 0
	v_mov_b32 v108, 0
	v_mov_b32 v88, 0
	v_mov_b32 v92, 0
	v_mov_b32 v64, 0
	v_mov_b32 v68, 0
	v_mov_b32 v56, 0
	v_mov_b32 v60, 0
	v_mov_b32 v32, 0
	v_mov_b32 v36, 0
	v_mov_b32 v16, 0
	v_mov_b32 v20, 0
	v_mov_b32 v0, 0
	v_mov_b32 v4, 0
	v_mov_b32 v76, 0
	v_mov_b32 v84, 0
	v_mov_b32 v44, 0
	v_mov_b32 v52, 0
	v_mov_b32 v24, 0
	v_mov_b32 v28, 0
	v_mov_b32 v8, 0
	v_mov_b32 v12, 0
	global_load_lds_dwordx4 v128, s[36:37]
	s_add_i32 m0, s20, 0x12000
	s_add_u32 s10, s36, 0x10000
	global_load_lds_dwordx4 v130, s[36:37]
	s_addc_u32 s11, s37, 0
	s_add_i32 m0, s20, 0x14000
	s_add_i32 s21, s20, 0x2000
	global_load_lds_dwordx4 v128, s[10:11]
	s_add_i32 m0, s20, 0x16000
	s_nop 0
	global_load_lds_dwordx4 v130, s[10:11]
	s_mov_b32 m0, s20
	s_add_u32 s10, s34, 0x10000
	global_load_lds_dwordx4 v134, s[34:35]
	s_mov_b32 m0, s21
	s_addc_u32 s11, s35, 0
	s_add_i32 s25, s20, 0x4000
	global_load_lds_dwordx4 v132, s[34:35]
	s_mov_b32 m0, s25
	s_add_i32 s42, s20, 0x6000
	global_load_lds_dwordx4 v134, s[10:11]
	s_mov_b32 m0, s42
	s_cmp_eq_u32 s14, 1
	global_load_lds_dwordx4 v132, s[10:11]
	s_cselect_b64 s[10:11], -1, 0
	s_cmp_lg_u32 s14, 1
	s_cbranch_scc1 .LBB0_338
	s_barrier

.LBB0_351:
	s_xor_b32 s62, s62, 0x78
	v_mov_b32_e32 v137, v191
	s_andn2_b64 vcc, exec, s[8:9]
	v_readfirstlane_b32 s7, v137
	s_cbranch_vccnz .LBB0_367
	v_lshlrev_b32_e32 v0, 4, v137
	v_add_u32_e32 v1, 0x2000, v0
	v_ashrrev_i32_e32 v2, 31, v1
	v_lshrrev_b32_e32 v2, 22, v2
	v_add_u32_e32 v2, v1, v2
	v_ashrrev_i32_e32 v2, 10, v2
	v_mul_i32_i24_e32 v3, 0x400, v2
	v_sub_u32_e32 v1, v1, v3
	v_lshrrev_b32_e32 v3, 4, v1
	v_bitop3_b32 v1, v3, v1, 32 bitop3:0x6c
	v_ashrrev_i32_e32 v3, 31, v1
	v_lshrrev_b32_e32 v3, 26, v3
	v_add_u32_e32 v3, v1, v3
	v_lshlrev_b32_e32 v5, 3, v2
	v_ashrrev_i32_e32 v4, 6, v3
	v_and_b32_e32 v5, -16, v5
	v_and_b32_e32 v3, 0xc0, v3
	v_add_u32_e32 v5, v4, v5
	v_sub_u32_e32 v1, v1, v3
	v_and_b32_e32 v4, 3, v4
	s_mov_b32 s6, 0x7fffe0
	v_lshrrev_b32_e32 v6, 2, v5
	v_lshlrev_b32_e32 v7, 1, v5
	v_lshlrev_b32_e32 v2, 5, v2
	v_ashrrev_i16_sdwa v1, v231, sext(v1) dst_sel:DWORD dst_unused:UNUSED_PAD src0_sel:DWORD src1_sel:BYTE_0
	v_and_or_b32 v4, v5, s6, v4
	v_and_b32_e32 v6, 4, v6
	v_and_b32_e32 v7, 24, v7
	v_and_b32_e32 v2, 32, v2
	v_bfe_i32 v1, v1, 0, 16
	v_or3_b32 v4, v4, v6, v7
	v_add_lshl_u32 v1, v2, v1, 1
	v_lshl_add_u32 v130, v4, 9, v1
	v_lshl_add_u32 v132, v5, 9, v1
	v_bfe_i32 v1, v137, 27, 1
	v_lshrrev_b32_e32 v1, 22, v1
	v_add_u32_e32 v1, v0, v1
	v_and_b32_e32 v1, 0xfffffc00, v1
	v_sub_u32_e32 v0, v0, v1
	v_lshrrev_b32_e32 v1, 4, v0
	v_ashrrev_i32_e32 v3, 31, v137
	v_bitop3_b32 v0, v1, v0, 32 bitop3:0x6c
	v_lshrrev_b32_e32 v3, 26, v3
	v_ashrrev_i32_e32 v1, 31, v0
	v_add_u32_e32 v3, v137, v3
	v_lshrrev_b32_e32 v1, 26, v1
	v_ashrrev_i32_e32 v3, 6, v3
	v_add_u32_e32 v1, v0, v1
	v_lshlrev_b32_e32 v4, 3, v3
	s_add_u32 s4, s67, 0x2420000
	v_ashrrev_i32_e32 v2, 6, v1
	v_and_b32_e32 v4, -16, v4
	s_addc_u32 s5, s94, 0
	v_add_u32_e32 v4, v2, v4
	v_and_b32_e32 v2, 3, v2
	s_ashr_i32 s41, s62, 31
	v_and_or_b32 v2, v4, s6, v2
	s_lshr_b32 s6, s41, 29
	s_add_i32 s6, s62, s6
	s_ashr_i32 s11, s7, 6
	s_and_b32 s8, s6, -8
	s_ashr_i32 s10, s7, 8
	s_lshl_b32 s40, s11, 10
	s_sub_i32 s8, s62, s8
	s_cmp_lt_i32 s8, 0
	s_movk_i32 s9, 0x45
	s_cselect_b32 s9, s9, 0x44
	s_mul_i32 s8, s8, s9
	s_ashr_i32 s6, s6, 3
	s_add_i32 s8, s8, s6
	s_mul_hi_i32 s6, s8, 0x78787879
	v_and_b32_e32 v1, 0xc0, v1
	s_lshr_b32 s9, s6, 31
	s_ashr_i32 s6, s6, 9
	v_sub_u32_e32 v0, v0, v1
	s_add_i32 s6, s6, s9
	v_lshrrev_b32_e32 v5, 2, v4
	v_lshlrev_b32_e32 v6, 1, v4
	v_lshlrev_b32_e32 v3, 5, v3
	v_ashrrev_i16_sdwa v0, v231, sext(v0) dst_sel:DWORD dst_unused:UNUSED_PAD src0_sel:DWORD src1_sel:BYTE_0
	s_lshl_b32 s12, s6, 3
	v_and_b32_e32 v5, 4, v5
	v_and_b32_e32 v6, 24, v6
	v_and_b32_e32 v3, 32, v3
	v_bfe_i32 v0, v0, 0, 16
	s_sub_i32 s9, 4, s12
	v_or3_b32 v2, v2, v5, v6
	v_add_lshl_u32 v0, v3, v0, 1
	s_min_u32 s13, s9, 8
	s_mulk_i32 s6, 0x440
	v_lshl_add_u32 v128, v2, 9, v0
	s_sub_i32 s14, s8, s6
	v_cvt_f32_ubyte0_e32 v2, s13
	v_cvt_f32_i32_e32 v1, s14
	v_rcp_iflag_f32_e32 v3, v2
	v_lshl_add_u32 v134, v4, 9, v0
	s_ashr_i32 s6, s14, 30
	s_or_b32 s6, s6, 1
	v_mul_f32_e32 v0, v1, v3
	v_trunc_f32_e32 v0, v0
	v_fma_f32 v1, -v0, v2, v1
	v_cvt_i32_f32_e32 v0, v0
	v_cmp_ge_f32_e64 s[8:9], |v1|, v2
	s_and_b64 s[8:9], s[8:9], exec
	s_cselect_b32 s6, s6, 0
	v_readfirstlane_b32 s8, v0
	s_add_i32 s6, s8, s6
	s_mul_i32 s8, s6, s13
	s_sub_i32 s8, s14, s8
	s_sext_i32_i16 s8, s8
	s_add_i32 s16, s12, s8
	s_ashr_i32 s17, s16, 31
	s_lshl_b64 s[8:9], s[16:17], 17
	s_add_u32 s18, s4, s8
	s_addc_u32 s19, s5, s9
	s_bfe_i64 s[8:9], s[6:7], 0x100000
	s_lshl_b64 s[8:9], s[8:9], 17
	s_add_u32 s24, s0, s8
	s_addc_u32 s25, s1, s9
	s_add_i32 s17, s40, 0
	s_add_i32 m0, s17, 0x10000
	s_waitcnt vmcnt(0)
	v_mov_b32 v108, 0
	v_mov_b32 v116, 0
	v_mov_b32 v92, 0
	v_mov_b32 v100, 0
	v_mov_b32 v68, 0
	v_mov_b32 v76, 0
	v_mov_b32 v40, 0
	v_mov_b32 v44, 0
	v_mov_b32 v120, 0
	v_mov_b32 v124, 0
	v_mov_b32 v104, 0
	v_mov_b32 v112, 0
	v_mov_b32 v88, 0
	v_mov_b32 v96, 0
	v_mov_b32 v64, 0
	v_mov_b32 v72, 0
	v_mov_b32 v52, 0
	v_mov_b32 v60, 0
	v_mov_b32 v28, 0
	v_mov_b32 v36, 0
	v_mov_b32 v12, 0
	v_mov_b32 v16, 0
	v_mov_b32 v0, 0
	v_mov_b32 v4, 0
	v_mov_b32 v80, 0
	v_mov_b32 v84, 0
	v_mov_b32 v48, 0
	v_mov_b32 v56, 0
	v_mov_b32 v24, 0
	v_mov_b32 v32, 0
	v_mov_b32 v8, 0
	v_mov_b32 v20, 0
	global_load_lds_dwordx4 v128, s[24:25]
	s_add_i32 m0, s17, 0x12000
	s_add_u32 s8, s24, 0x10000
	global_load_lds_dwordx4 v130, s[24:25]
	s_addc_u32 s9, s25, 0
	s_add_i32 m0, s17, 0x14000
	s_add_i32 s20, s17, 0x2000
	global_load_lds_dwordx4 v128, s[8:9]
	s_add_i32 m0, s17, 0x16000
	v_mov_b32_e32 v131, v129
	global_load_lds_dwordx4 v130, s[8:9]
	s_mov_b32 m0, s17
	s_add_u32 s8, s18, 0x10000
	global_load_lds_dwordx4 v134, s[18:19]
	s_mov_b32 m0, s20
	s_addc_u32 s9, s19, 0
	s_add_i32 s21, s17, 0x4000
	global_load_lds_dwordx4 v132, s[18:19]
	s_mov_b32 m0, s21
	s_add_i32 s42, s17, 0x6000
	global_load_lds_dwordx4 v134, s[8:9]
	s_mov_b32 m0, s42
	v_mov_b32_e32 v135, v129
	global_load_lds_dwordx4 v132, s[8:9]
	v_mov_b32_e32 v133, v129
	s_cmp_eq_u32 s10, 1
	v_lshl_add_u64 v[14:15], s[24:25], 0, v[128:129]
	v_lshl_add_u64 v[10:11], s[24:25], 0, v[130:131]
	v_lshl_add_u64 v[2:3], s[18:19], 0, v[134:135]
	s_cselect_b64 s[8:9], -1, 0
	s_cmp_lg_u32 s10, 1
	v_lshl_add_u64 v[6:7], s[18:19], 0, v[132:133]
	s_cbranch_scc1 .LBB0_354
	s_barrier
